# P5/P6 K-loops: loader issues no VALU (DMA address copies and 64-bit VALU adds replaced by direct VGPR + SALU base), mid-burst setprio flips dropped
# baseline (speedup 1.0000x reference)
; #define PG8_LDA(dst, b, h) do { if constexpr (FP8) { _Pragma("unroll") for (int m = 0; m < 4; ++m) dst##8[m] = PG8_LD8(PG8_SA(b, h), aoff, aoff1, m); } \
;         else { _Pragma("unroll") for (int m = 0; m < 4; ++m) _Pragma("unroll") for (int k = 0; k < 2; ++k) dst[m][k] = *(const LAS bf16x8*)(lds + PG8_SA(b, h) + (k ? aoff1 : aoff) + m * 2048); } } while (0)
; #define PG8_LDB(dst, b, h) do { if constexpr (FP8) { dst##8[0] = PG8_LD8(PG8_SB(b, h), boff, boff1, 0); dst##8[1] = PG8_LD8(PG8_SB(b, h), boff, boff1, 1); } \
;         else { _Pragma("unroll") for (int n = 0; n < 2; ++n) _Pragma("unroll") for (int k = 0; k < 2; ++k) dst[n][k] = *(const LAS bf16x8*)(lds + PG8_SB(b, h) + (k ? boff1 : boff) + n * 2048); } } while (0)
; #define PG8_WAIT_V(n) asm volatile("s_waitcnt vmcnt(" #n ")" ::: "memory")
; #define PG8_WAIT_L(n) asm volatile("s_waitcnt lgkmcnt(" #n ")" ::: "memory")
; #define PG8_BAR __builtin_amdgcn_s_barrier()
; #define PG8_SCHED __builtin_amdgcn_sched_barrier(0)
; #define PG8_S1 PG8_STAGE(PG8_SA(1, 1), a1 + hstepA, voffA)
; #define PG8_S2 do { PG8_STAGE(PG8_SB(0, 0), b2, voffB); PG8_STAGE(PG8_SB(0, 1), b2 + hstepB, voffB); PG8_STAGE(PG8_SA(0, 0), a2, voffA); } while (0)
; template <class Epi, class SchedT, bool ALIGN_EPI, bool SP2, bool FP8 = false>
; __device__ __forceinline__ void gemm_phase(LAS unsigned char* lds, const Gemm g, const SchedT& S, const Epi& E, const int wid) {
;     ...
;             const bool last = (t == nt - 2);
;             const char* a1 = cA + (size_t)(t + 1) * kstep;
;             const char* a2 = last ? nA : cA + (size_t)(t + 2) * kstep; const char* b2 = last ? nB : cB + (size_t)(t + 2) * kstep;
;             const char* a3 = a2 + kstep; const char* b3 = b2 + kstep;
;             if constexpr (SP2) {
;     ...
;             PG8_LDB(B0, 0, 0); PG8_LDB(B1, 0, 1); PG8_SCHED; PG8_LDA(At, 0, 0); PG8_S1;
;             PG8_WAIT_V(8); PG8_WAIT_L(0); PG8_BAR; PG8_MMAP(0, 0, 0); PG8_BAR; PG8_SCHED;
;             PG8_LDA(At, 0, 1); PG8_S2;
;             PG8_WAIT_V(8); PG8_WAIT_L(0); PG8_BAR; PG8_MMAP(1, 0, 1); PG8_BAR; PG8_SCHED;
.LBB0_899:
	ds_read_b128 v[128:131], v173
	ds_read_b128 v[132:135], v173 offset:1024
	ds_read_b128 v[136:139], v174
	ds_read_b128 v[140:143], v174 offset:1024
	ds_read_b128 v[150:153], v175
	ds_read_b128 v[154:157], v175 offset:1024
	ds_read_b128 v[158:161], v176
	ds_read_b128 v[162:165], v176 offset:1024
	s_add_i32 s35, s34, 2
	s_add_u32 s16, s48, 0xfffc0080
	s_addc_u32 s17, s49, -1
	s_cmp_eq_u32 s27, s34
	s_cselect_b32 s51, s15, s17
	s_cselect_b32 s50, s21, s16
	s_cselect_b32 s53, s24, s31
	s_cselect_b32 s52, s25, s30
	ds_read_b128 v[182:185], v177
	ds_read_b128 v[186:189], v177 offset:1024
	ds_read_b128 v[190:193], v177 offset:2048
	ds_read_b128 v[194:197], v177 offset:3072
	ds_read_b128 v[198:201], v177 offset:4096
	ds_read_b128 v[202:205], v177 offset:5120
	ds_read_b128 v[206:209], v177 offset:6144
	ds_read_b128 v[210:213], v177 offset:7168
	s_add_i32 m0, s87, 0xc000
	s_nop 0
	global_load_lds_dwordx4 v168, s[48:49]
	s_add_i32 m0, s87, 0xe000
	s_nop 0
	global_load_lds_dwordx4 v170, s[48:49]
	s_waitcnt vmcnt(8)
	s_waitcnt lgkmcnt(0)
	s_barrier
	s_setprio 1
	s_waitcnt lgkmcnt(0)
	v_mfma_f32_16x16x32_bf16 v[124:127], v[128:131], v[182:185], v[124:127]
	v_mfma_f32_16x16x32_bf16 v[120:123], v[136:139], v[182:185], v[120:123]
	v_mfma_f32_16x16x32_bf16 v[108:111], v[128:131], v[190:193], v[108:111]
	v_mfma_f32_16x16x32_bf16 v[104:107], v[136:139], v[190:193], v[104:107]
	v_mfma_f32_16x16x32_bf16 v[92:95], v[128:131], v[198:201], v[92:95]
	v_mfma_f32_16x16x32_bf16 v[88:91], v[136:139], v[198:201], v[88:91]
	v_mfma_f32_16x16x32_bf16 v[76:79], v[128:131], v[206:209], v[76:79]
	v_mfma_f32_16x16x32_bf16 v[72:75], v[136:139], v[206:209], v[72:75]
	v_mfma_f32_16x16x32_bf16 v[124:127], v[132:135], v[186:189], v[124:127]
	v_mfma_f32_16x16x32_bf16 v[120:123], v[140:143], v[186:189], v[120:123]
	v_mfma_f32_16x16x32_bf16 v[108:111], v[132:135], v[194:197], v[108:111]
	v_mfma_f32_16x16x32_bf16 v[104:107], v[140:143], v[194:197], v[104:107]
	v_mfma_f32_16x16x32_bf16 v[92:95], v[132:135], v[202:205], v[92:95]
	v_mfma_f32_16x16x32_bf16 v[88:91], v[140:143], v[202:205], v[88:91]
	v_mfma_f32_16x16x32_bf16 v[76:79], v[132:135], v[210:213], v[76:79]
	v_mfma_f32_16x16x32_bf16 v[72:75], v[140:143], v[210:213], v[72:75]
	v_mfma_f32_16x16x32_bf16 v[116:119], v[150:153], v[182:185], v[116:119]
	v_mfma_f32_16x16x32_bf16 v[112:115], v[158:161], v[182:185], v[112:115]
	v_mfma_f32_16x16x32_bf16 v[100:103], v[150:153], v[190:193], v[100:103]
	v_mfma_f32_16x16x32_bf16 v[96:99], v[158:161], v[190:193], v[96:99]
	v_mfma_f32_16x16x32_bf16 v[84:87], v[150:153], v[198:201], v[84:87]
	v_mfma_f32_16x16x32_bf16 v[80:83], v[158:161], v[198:201], v[80:83]
	v_mfma_f32_16x16x32_bf16 v[68:71], v[150:153], v[206:209], v[68:71]
	v_mfma_f32_16x16x32_bf16 v[64:67], v[158:161], v[206:209], v[64:67]
	v_mfma_f32_16x16x32_bf16 v[116:119], v[154:157], v[186:189], v[116:119]
	v_mfma_f32_16x16x32_bf16 v[112:115], v[162:165], v[186:189], v[112:115]
	v_mfma_f32_16x16x32_bf16 v[100:103], v[154:157], v[194:197], v[100:103]
	v_mfma_f32_16x16x32_bf16 v[96:99], v[162:165], v[194:197], v[96:99]
	v_mfma_f32_16x16x32_bf16 v[84:87], v[154:157], v[202:205], v[84:87]
	v_mfma_f32_16x16x32_bf16 v[80:83], v[162:165], v[202:205], v[80:83]
	v_mfma_f32_16x16x32_bf16 v[68:71], v[154:157], v[210:213], v[68:71]
	v_mfma_f32_16x16x32_bf16 v[64:67], v[162:165], v[210:213], v[64:67]
	s_setprio 0
	s_barrier
	s_add_i32 s16, s94, s86
	ds_read_b128 v[182:185], v177 offset:16384
	ds_read_b128 v[186:189], v177 offset:17408
	ds_read_b128 v[190:193], v177 offset:18432
	ds_read_b128 v[194:197], v177 offset:19456
	ds_read_b128 v[198:201], v177 offset:20480
	ds_read_b128 v[202:205], v177 offset:21504
	ds_read_b128 v[206:209], v177 offset:22528
	ds_read_b128 v[210:213], v177 offset:23552
	s_mov_b32 m0, s16
	s_nop 0
	global_load_lds_dwordx4 v169, s[52:53]
	s_add_i32 m0, s16, 0x2000
	s_add_u32 s60, s52, 0x40000
	global_load_lds_dwordx4 v171, s[52:53]
	s_addc_u32 s61, s53, 0
	s_add_i32 s16, s95, s86
	s_mov_b32 m0, s16
	s_nop 0
	global_load_lds_dwordx4 v169, s[60:61]
	s_add_i32 m0, s16, 0x2000
	s_nop 0
	global_load_lds_dwordx4 v171, s[60:61]
	s_mov_b32 m0, s87
	s_nop 0
	global_load_lds_dwordx4 v168, s[50:51]
	s_mov_b32 m0, s88
	s_nop 0
	global_load_lds_dwordx4 v170, s[50:51]
	s_waitcnt vmcnt(8)
	s_waitcnt lgkmcnt(0)
	s_barrier
	s_setprio 1
	s_waitcnt lgkmcnt(0)
	v_mfma_f32_16x16x32_bf16 v[60:63], v[128:131], v[182:185], v[60:63]
	v_mfma_f32_16x16x32_bf16 v[56:59], v[136:139], v[182:185], v[56:59]
	v_mfma_f32_16x16x32_bf16 v[44:47], v[128:131], v[190:193], v[44:47]
	v_mfma_f32_16x16x32_bf16 v[40:43], v[136:139], v[190:193], v[40:43]
	v_mfma_f32_16x16x32_bf16 v[28:31], v[128:131], v[198:201], v[28:31]
	v_mfma_f32_16x16x32_bf16 v[24:27], v[136:139], v[198:201], v[24:27]
	v_mfma_f32_16x16x32_bf16 v[12:15], v[128:131], v[206:209], v[12:15]
	v_mfma_f32_16x16x32_bf16 v[8:11], v[136:139], v[206:209], v[8:11]
	v_mfma_f32_16x16x32_bf16 v[60:63], v[132:135], v[186:189], v[60:63]
	v_mfma_f32_16x16x32_bf16 v[56:59], v[140:143], v[186:189], v[56:59]
	v_mfma_f32_16x16x32_bf16 v[44:47], v[132:135], v[194:197], v[44:47]
	v_mfma_f32_16x16x32_bf16 v[40:43], v[140:143], v[194:197], v[40:43]
	v_mfma_f32_16x16x32_bf16 v[28:31], v[132:135], v[202:205], v[28:31]
	v_mfma_f32_16x16x32_bf16 v[24:27], v[140:143], v[202:205], v[24:27]
	v_mfma_f32_16x16x32_bf16 v[12:15], v[132:135], v[210:213], v[12:15]
	v_mfma_f32_16x16x32_bf16 v[8:11], v[140:143], v[210:213], v[8:11]
	v_mfma_f32_16x16x32_bf16 v[52:55], v[150:153], v[182:185], v[52:55]
	v_mfma_f32_16x16x32_bf16 v[48:51], v[158:161], v[182:185], v[48:51]
	v_mfma_f32_16x16x32_bf16 v[36:39], v[150:153], v[190:193], v[36:39]
	v_mfma_f32_16x16x32_bf16 v[32:35], v[158:161], v[190:193], v[32:35]
	v_mfma_f32_16x16x32_bf16 v[20:23], v[150:153], v[198:201], v[20:23]
	v_mfma_f32_16x16x32_bf16 v[16:19], v[158:161], v[198:201], v[16:19]
	v_mfma_f32_16x16x32_bf16 v[4:7], v[150:153], v[206:209], v[4:7]
	v_mfma_f32_16x16x32_bf16 v[0:3], v[158:161], v[206:209], v[0:3]
	v_mfma_f32_16x16x32_bf16 v[52:55], v[154:157], v[186:189], v[52:55]
	v_mfma_f32_16x16x32_bf16 v[48:51], v[162:165], v[186:189], v[48:51]
	v_mfma_f32_16x16x32_bf16 v[36:39], v[154:157], v[194:197], v[36:39]
	v_mfma_f32_16x16x32_bf16 v[32:35], v[162:165], v[194:197], v[32:35]
	v_mfma_f32_16x16x32_bf16 v[20:23], v[154:157], v[202:205], v[20:23]
	v_mfma_f32_16x16x32_bf16 v[16:19], v[162:165], v[202:205], v[16:19]
	v_mfma_f32_16x16x32_bf16 v[4:7], v[154:157], v[210:213], v[4:7]
	v_mfma_f32_16x16x32_bf16 v[0:3], v[162:165], v[210:213], v[0:3]
	s_setprio 0
	s_barrier
; #define PG8_LDA(dst, b, h) do { if constexpr (FP8) { _Pragma("unroll") for (int m = 0; m < 4; ++m) dst##8[m] = PG8_LD8(PG8_SA(b, h), aoff, aoff1, m); } \
;         else { _Pragma("unroll") for (int m = 0; m < 4; ++m) _Pragma("unroll") for (int k = 0; k < 2; ++k) dst[m][k] = *(const LAS bf16x8*)(lds + PG8_SA(b, h) + (k ? aoff1 : aoff) + m * 2048); } } while (0)
; #define PG8_LDB(dst, b, h) do { if constexpr (FP8) { dst##8[0] = PG8_LD8(PG8_SB(b, h), boff, boff1, 0); dst##8[1] = PG8_LD8(PG8_SB(b, h), boff, boff1, 1); } \
;         else { _Pragma("unroll") for (int n = 0; n < 2; ++n) _Pragma("unroll") for (int k = 0; k < 2; ++k) dst[n][k] = *(const LAS bf16x8*)(lds + PG8_SB(b, h) + (k ? boff1 : boff) + n * 2048); } } while (0)
; #define PG8_WAIT_V(n) asm volatile("s_waitcnt vmcnt(" #n ")" ::: "memory")
; #define PG8_WAIT_L(n) asm volatile("s_waitcnt lgkmcnt(" #n ")" ::: "memory")
; #define PG8_BAR __builtin_amdgcn_s_barrier()
; #define PG8_SCHED __builtin_amdgcn_sched_barrier(0)
; #define PG8_S3 PG8_STAGE(PG8_SA(0, 1), a2 + hstepA, voffA)
; #define PG8_S4 do { PG8_STAGE(PG8_SB(1, 0), b3, voffB); PG8_STAGE(PG8_SB(1, 1), b3 + hstepB, voffB); PG8_STAGE(PG8_SA(1, 0), a3, voffA); } while (0)
; template <class Epi, class SchedT, bool ALIGN_EPI, bool SP2, bool FP8 = false>
; __device__ __forceinline__ void gemm_phase(LAS unsigned char* lds, const Gemm g, const SchedT& S, const Epi& E, const int wid) {
;     ...
;         for (int t = 0; t < nt; t += 2) {
;     ...
;             PG8_LDB(B0, 1, 0); PG8_LDB(B1, 1, 1); PG8_SCHED; PG8_LDA(At, 1, 0); PG8_S3;
;             PG8_WAIT_V(8); PG8_WAIT_L(0); PG8_BAR; PG8_MMAP(0, 1, 0); PG8_BAR; PG8_SCHED;
;             PG8_LDA(At, 1, 1); PG8_S4;
;             PG8_WAIT_V(8); PG8_WAIT_L(0); PG8_BAR; PG8_MMAP(1, 1, 1); PG8_BAR; PG8_SCHED;
	s_add_i32 s16, 0, 0x18000
	s_add_i32 s17, 0, 0x1c000
	v_add_u32_e32 v132, s16, v172
	v_add_u32_e32 v144, s17, v172
	ds_read_b128 v[128:131], v132
	ds_read_b128 v[132:135], v132 offset:1024
	ds_read_b128 v[136:139], v178
	ds_read_b128 v[140:143], v178 offset:1024
	ds_read_b128 v[150:153], v144
	ds_read_b128 v[154:157], v144 offset:1024
	ds_read_b128 v[158:161], v179
	ds_read_b128 v[162:165], v179 offset:1024
	s_add_u32 s60, s50, 0x40000
	s_mov_b32 m0, s89
	ds_read_b128 v[182:185], v177 offset:32768
	ds_read_b128 v[186:189], v177 offset:33792
	ds_read_b128 v[190:193], v177 offset:34816
	ds_read_b128 v[194:197], v177 offset:35840
	ds_read_b128 v[198:201], v177 offset:36864
	ds_read_b128 v[202:205], v177 offset:37888
	ds_read_b128 v[206:209], v177 offset:38912
	ds_read_b128 v[210:213], v177 offset:39936
	s_addc_u32 s61, s51, 0
	s_nop 0
	global_load_lds_dwordx4 v168, s[60:61]
	s_mov_b32 m0, s90
	s_nop 0
	global_load_lds_dwordx4 v170, s[60:61]
	s_waitcnt vmcnt(8)
	s_waitcnt lgkmcnt(0)
	s_barrier
	s_setprio 1
	s_waitcnt lgkmcnt(0)
	v_mfma_f32_16x16x32_bf16 v[124:127], v[128:131], v[182:185], v[124:127]
	v_mfma_f32_16x16x32_bf16 v[120:123], v[136:139], v[182:185], v[120:123]
	v_mfma_f32_16x16x32_bf16 v[108:111], v[128:131], v[190:193], v[108:111]
	v_mfma_f32_16x16x32_bf16 v[104:107], v[136:139], v[190:193], v[104:107]
	v_mfma_f32_16x16x32_bf16 v[92:95], v[128:131], v[198:201], v[92:95]
	v_mfma_f32_16x16x32_bf16 v[88:91], v[136:139], v[198:201], v[88:91]
	v_mfma_f32_16x16x32_bf16 v[76:79], v[128:131], v[206:209], v[76:79]
	v_mfma_f32_16x16x32_bf16 v[72:75], v[136:139], v[206:209], v[72:75]
	v_mfma_f32_16x16x32_bf16 v[124:127], v[132:135], v[186:189], v[124:127]
	v_mfma_f32_16x16x32_bf16 v[120:123], v[140:143], v[186:189], v[120:123]
	v_mfma_f32_16x16x32_bf16 v[108:111], v[132:135], v[194:197], v[108:111]
	v_mfma_f32_16x16x32_bf16 v[104:107], v[140:143], v[194:197], v[104:107]
	v_mfma_f32_16x16x32_bf16 v[92:95], v[132:135], v[202:205], v[92:95]
	v_mfma_f32_16x16x32_bf16 v[88:91], v[140:143], v[202:205], v[88:91]
	v_mfma_f32_16x16x32_bf16 v[76:79], v[132:135], v[210:213], v[76:79]
	v_mfma_f32_16x16x32_bf16 v[72:75], v[140:143], v[210:213], v[72:75]
	v_mfma_f32_16x16x32_bf16 v[116:119], v[150:153], v[182:185], v[116:119]
	v_mfma_f32_16x16x32_bf16 v[112:115], v[158:161], v[182:185], v[112:115]
	v_mfma_f32_16x16x32_bf16 v[100:103], v[150:153], v[190:193], v[100:103]
	v_mfma_f32_16x16x32_bf16 v[96:99], v[158:161], v[190:193], v[96:99]
	v_mfma_f32_16x16x32_bf16 v[84:87], v[150:153], v[198:201], v[84:87]
	v_mfma_f32_16x16x32_bf16 v[80:83], v[158:161], v[198:201], v[80:83]
	v_mfma_f32_16x16x32_bf16 v[68:71], v[150:153], v[206:209], v[68:71]
	v_mfma_f32_16x16x32_bf16 v[64:67], v[158:161], v[206:209], v[64:67]
	v_mfma_f32_16x16x32_bf16 v[116:119], v[154:157], v[186:189], v[116:119]
	v_mfma_f32_16x16x32_bf16 v[112:115], v[162:165], v[186:189], v[112:115]
	v_mfma_f32_16x16x32_bf16 v[100:103], v[154:157], v[194:197], v[100:103]
	v_mfma_f32_16x16x32_bf16 v[96:99], v[162:165], v[194:197], v[96:99]
	v_mfma_f32_16x16x32_bf16 v[84:87], v[154:157], v[202:205], v[84:87]
	v_mfma_f32_16x16x32_bf16 v[80:83], v[162:165], v[202:205], v[80:83]
	v_mfma_f32_16x16x32_bf16 v[68:71], v[154:157], v[210:213], v[68:71]
	v_mfma_f32_16x16x32_bf16 v[64:67], v[162:165], v[210:213], v[64:67]
	s_setprio 0
	s_barrier
	ds_read_b128 v[182:185], v177 offset:49152
	ds_read_b128 v[186:189], v177 offset:50176
	ds_read_b128 v[190:193], v177 offset:51200
	ds_read_b128 v[194:197], v177 offset:52224
	ds_read_b128 v[198:201], v177 offset:53248
	ds_read_b128 v[202:205], v177 offset:54272
	ds_read_b128 v[206:209], v177 offset:55296
	ds_read_b128 v[210:213], v177 offset:56320
	s_add_i32 s16, s16, s86
	s_add_u32 s98, s52, s6
	s_addc_u32 s99, s53, s7
	s_mov_b32 m0, s16
	s_nop 0
	global_load_lds_dwordx4 v169, s[98:99]
	s_add_i32 m0, s16, 0x2000
	s_nop 0
	s_add_u32 s52, s52, 0x40080
	s_addc_u32 s53, s53, 0
	s_add_i32 s16, s17, s86
	global_load_lds_dwordx4 v171, s[98:99]
	s_mov_b32 m0, s16
	s_nop 0
	global_load_lds_dwordx4 v169, s[52:53]
	s_add_i32 m0, s16, 0x2000
	s_nop 0
	global_load_lds_dwordx4 v171, s[52:53]
	s_mov_b32 m0, s92
	s_add_u32 s100, s50, s6
	s_addc_u32 s101, s51, s7
	global_load_lds_dwordx4 v168, s[100:101]
	s_mov_b32 m0, s93
	s_nop 0
	global_load_lds_dwordx4 v170, s[100:101]
	s_waitcnt vmcnt(8)
	s_waitcnt lgkmcnt(0)
	s_barrier
	s_setprio 1
	s_waitcnt lgkmcnt(0)
	v_mfma_f32_16x16x32_bf16 v[60:63], v[128:131], v[182:185], v[60:63]
	v_mfma_f32_16x16x32_bf16 v[56:59], v[136:139], v[182:185], v[56:59]
	v_mfma_f32_16x16x32_bf16 v[44:47], v[128:131], v[190:193], v[44:47]
	v_mfma_f32_16x16x32_bf16 v[40:43], v[136:139], v[190:193], v[40:43]
	v_mfma_f32_16x16x32_bf16 v[28:31], v[128:131], v[198:201], v[28:31]
	v_mfma_f32_16x16x32_bf16 v[24:27], v[136:139], v[198:201], v[24:27]
	v_mfma_f32_16x16x32_bf16 v[12:15], v[128:131], v[206:209], v[12:15]
	v_mfma_f32_16x16x32_bf16 v[8:11], v[136:139], v[206:209], v[8:11]
	v_mfma_f32_16x16x32_bf16 v[60:63], v[132:135], v[186:189], v[60:63]
	v_mfma_f32_16x16x32_bf16 v[56:59], v[140:143], v[186:189], v[56:59]
	v_mfma_f32_16x16x32_bf16 v[44:47], v[132:135], v[194:197], v[44:47]
	v_mfma_f32_16x16x32_bf16 v[40:43], v[140:143], v[194:197], v[40:43]
	v_mfma_f32_16x16x32_bf16 v[28:31], v[132:135], v[202:205], v[28:31]
	v_mfma_f32_16x16x32_bf16 v[24:27], v[140:143], v[202:205], v[24:27]
	v_mfma_f32_16x16x32_bf16 v[12:15], v[132:135], v[210:213], v[12:15]
	v_mfma_f32_16x16x32_bf16 v[8:11], v[140:143], v[210:213], v[8:11]
	v_mfma_f32_16x16x32_bf16 v[52:55], v[150:153], v[182:185], v[52:55]
	v_mfma_f32_16x16x32_bf16 v[48:51], v[158:161], v[182:185], v[48:51]
	v_mfma_f32_16x16x32_bf16 v[36:39], v[150:153], v[190:193], v[36:39]
	v_mfma_f32_16x16x32_bf16 v[32:35], v[158:161], v[190:193], v[32:35]
	v_mfma_f32_16x16x32_bf16 v[20:23], v[150:153], v[198:201], v[20:23]
	v_mfma_f32_16x16x32_bf16 v[16:19], v[158:161], v[198:201], v[16:19]
	v_mfma_f32_16x16x32_bf16 v[4:7], v[150:153], v[206:209], v[4:7]
	v_mfma_f32_16x16x32_bf16 v[0:3], v[158:161], v[206:209], v[0:3]
	v_mfma_f32_16x16x32_bf16 v[52:55], v[154:157], v[186:189], v[52:55]
	v_mfma_f32_16x16x32_bf16 v[48:51], v[162:165], v[186:189], v[48:51]
	v_mfma_f32_16x16x32_bf16 v[36:39], v[154:157], v[194:197], v[36:39]
	v_mfma_f32_16x16x32_bf16 v[32:35], v[162:165], v[194:197], v[32:35]
	v_mfma_f32_16x16x32_bf16 v[20:23], v[154:157], v[202:205], v[20:23]
	v_mfma_f32_16x16x32_bf16 v[16:19], v[162:165], v[202:205], v[16:19]
	v_mfma_f32_16x16x32_bf16 v[4:7], v[154:157], v[210:213], v[4:7]
	v_mfma_f32_16x16x32_bf16 v[0:3], v[162:165], v[210:213], v[0:3]
	s_setprio 0
	s_barrier
	s_add_u32 s48, s48, 0x100
	s_addc_u32 s49, s49, 0
	s_add_u32 s30, s30, 0x100
	s_addc_u32 s31, s31, 0
	s_cmp_ge_i32 s35, s20
	s_mov_b32 s34, s35
	s_cbranch_scc0 .LBB0_899
	s_branch .LBB0_894

; #define PG8_LDA(dst, b, h) do { if constexpr (FP8) { _Pragma("unroll") for (int m = 0; m < 4; ++m) dst##8[m] = PG8_LD8(PG8_SA(b, h), aoff, aoff1, m); } \
;         else { _Pragma("unroll") for (int m = 0; m < 4; ++m) _Pragma("unroll") for (int k = 0; k < 2; ++k) dst[m][k] = *(const LAS bf16x8*)(lds + PG8_SA(b, h) + (k ? aoff1 : aoff) + m * 2048); } } while (0)
; #define PG8_LDB(dst, b, h) do { if constexpr (FP8) { dst##8[0] = PG8_LD8(PG8_SB(b, h), boff, boff1, 0); dst##8[1] = PG8_LD8(PG8_SB(b, h), boff, boff1, 1); } \
;         else { _Pragma("unroll") for (int n = 0; n < 2; ++n) _Pragma("unroll") for (int k = 0; k < 2; ++k) dst[n][k] = *(const LAS bf16x8*)(lds + PG8_SB(b, h) + (k ? boff1 : boff) + n * 2048); } } while (0)
; #define PG8_WAIT_V(n) asm volatile("s_waitcnt vmcnt(" #n ")" ::: "memory")
; #define PG8_WAIT_L(n) asm volatile("s_waitcnt lgkmcnt(" #n ")" ::: "memory")
; #define PG8_BAR __builtin_amdgcn_s_barrier()
; #define PG8_SCHED __builtin_amdgcn_sched_barrier(0)
; #define PG8_S1 PG8_STAGE(PG8_SA(1, 1), a1 + hstepA, voffA)
; #define PG8_S2 do { PG8_STAGE(PG8_SB(0, 0), b2, voffB); PG8_STAGE(PG8_SB(0, 1), b2 + hstepB, voffB); PG8_STAGE(PG8_SA(0, 0), a2, voffA); } while (0)
; template <class Epi, class SchedT, bool ALIGN_EPI, bool SP2, bool FP8 = false>
; __device__ __forceinline__ void gemm_phase(LAS unsigned char* lds, const Gemm g, const SchedT& S, const Epi& E, const int wid) {
;     ...
;             const bool last = (t == nt - 2);
;             const char* a1 = cA + (size_t)(t + 1) * kstep;
;             const char* a2 = last ? nA : cA + (size_t)(t + 2) * kstep; const char* b2 = last ? nB : cB + (size_t)(t + 2) * kstep;
;             const char* a3 = a2 + kstep; const char* b3 = b2 + kstep;
;             if constexpr (SP2) {
;     ...
;             PG8_LDB(B0, 0, 0); PG8_LDB(B1, 0, 1); PG8_SCHED; PG8_LDA(At, 0, 0); PG8_S1;
;             PG8_WAIT_V(8); PG8_WAIT_L(0); PG8_BAR; PG8_MMAP(0, 0, 0); PG8_BAR; PG8_SCHED;
;             PG8_LDA(At, 0, 1); PG8_S2;
;             PG8_WAIT_V(8); PG8_WAIT_L(0); PG8_BAR; PG8_MMAP(1, 0, 1); PG8_BAR; PG8_SCHED;
.LBB0_970:
	ds_read_b128 v[134:137], v175
	ds_read_b128 v[138:141], v175 offset:1024
	ds_read_b128 v[142:145], v176
	ds_read_b128 v[146:149], v176 offset:1024
	ds_read_b128 v[150:153], v177
	ds_read_b128 v[154:157], v177 offset:1024
	ds_read_b128 v[158:161], v178
	ds_read_b128 v[162:165], v178 offset:1024
	s_add_i32 s48, s34, 2
	s_add_u32 s16, s24, 0xfff00080
	s_addc_u32 s17, s25, -1
	s_cmp_eq_u32 s45, s34
	s_cselect_b32 s34, s15, s16
	s_cselect_b32 s35, s13, s17
	s_cselect_b32 s39, s27, s47
	s_cselect_b32 s38, s31, s46
	ds_read_b128 v[166:169], v179
	ds_read_b128 v[184:187], v179 offset:1024
	ds_read_b128 v[188:191], v179 offset:2048
	ds_read_b128 v[192:195], v179 offset:3072
	ds_read_b128 v[196:199], v179 offset:4096
	ds_read_b128 v[200:203], v179 offset:5120
	ds_read_b128 v[204:207], v179 offset:6144
	ds_read_b128 v[208:211], v179 offset:7168
	s_add_i32 m0, s87, 0xc000
	s_nop 0
	global_load_lds_dwordx4 v172, s[24:25]
	s_add_i32 m0, s87, 0xe000
	s_nop 0
	global_load_lds_dwordx4 v173, s[24:25]
	s_waitcnt vmcnt(8)
	s_waitcnt lgkmcnt(0)
	s_barrier
	s_setprio 1
	s_waitcnt lgkmcnt(0)
	v_mfma_f32_16x16x32_bf16 v[124:127], v[134:137], v[166:169], v[124:127]
	v_mfma_f32_16x16x32_bf16 v[120:123], v[142:145], v[166:169], v[120:123]
	v_mfma_f32_16x16x32_bf16 v[108:111], v[134:137], v[188:191], v[108:111]
	v_mfma_f32_16x16x32_bf16 v[104:107], v[142:145], v[188:191], v[104:107]
	v_mfma_f32_16x16x32_bf16 v[92:95], v[134:137], v[196:199], v[92:95]
	v_mfma_f32_16x16x32_bf16 v[88:91], v[142:145], v[196:199], v[88:91]
	v_mfma_f32_16x16x32_bf16 v[76:79], v[134:137], v[204:207], v[76:79]
	v_mfma_f32_16x16x32_bf16 v[72:75], v[142:145], v[204:207], v[72:75]
	v_mfma_f32_16x16x32_bf16 v[124:127], v[138:141], v[184:187], v[124:127]
	v_mfma_f32_16x16x32_bf16 v[120:123], v[146:149], v[184:187], v[120:123]
	v_mfma_f32_16x16x32_bf16 v[108:111], v[138:141], v[192:195], v[108:111]
	v_mfma_f32_16x16x32_bf16 v[104:107], v[146:149], v[192:195], v[104:107]
	v_mfma_f32_16x16x32_bf16 v[92:95], v[138:141], v[200:203], v[92:95]
	v_mfma_f32_16x16x32_bf16 v[88:91], v[146:149], v[200:203], v[88:91]
	v_mfma_f32_16x16x32_bf16 v[76:79], v[138:141], v[208:211], v[76:79]
	v_mfma_f32_16x16x32_bf16 v[72:75], v[146:149], v[208:211], v[72:75]
	v_mfma_f32_16x16x32_bf16 v[116:119], v[150:153], v[166:169], v[116:119]
	v_mfma_f32_16x16x32_bf16 v[112:115], v[158:161], v[166:169], v[112:115]
	v_mfma_f32_16x16x32_bf16 v[100:103], v[150:153], v[188:191], v[100:103]
	v_mfma_f32_16x16x32_bf16 v[96:99], v[158:161], v[188:191], v[96:99]
	v_mfma_f32_16x16x32_bf16 v[84:87], v[150:153], v[196:199], v[84:87]
	v_mfma_f32_16x16x32_bf16 v[80:83], v[158:161], v[196:199], v[80:83]
	v_mfma_f32_16x16x32_bf16 v[68:71], v[150:153], v[204:207], v[68:71]
	v_mfma_f32_16x16x32_bf16 v[64:67], v[158:161], v[204:207], v[64:67]
	v_mfma_f32_16x16x32_bf16 v[116:119], v[154:157], v[184:187], v[116:119]
	v_mfma_f32_16x16x32_bf16 v[112:115], v[162:165], v[184:187], v[112:115]
	v_mfma_f32_16x16x32_bf16 v[100:103], v[154:157], v[192:195], v[100:103]
	v_mfma_f32_16x16x32_bf16 v[96:99], v[162:165], v[192:195], v[96:99]
	v_mfma_f32_16x16x32_bf16 v[84:87], v[154:157], v[200:203], v[84:87]
	v_mfma_f32_16x16x32_bf16 v[80:83], v[162:165], v[200:203], v[80:83]
	v_mfma_f32_16x16x32_bf16 v[68:71], v[154:157], v[208:211], v[68:71]
	v_mfma_f32_16x16x32_bf16 v[64:67], v[162:165], v[208:211], v[64:67]
	s_setprio 0
	s_barrier
	s_add_i32 s16, s94, s86
	ds_read_b128 v[166:169], v179 offset:16384
	ds_read_b128 v[184:187], v179 offset:17408
	ds_read_b128 v[188:191], v179 offset:18432
	ds_read_b128 v[192:195], v179 offset:19456
	ds_read_b128 v[196:199], v179 offset:20480
	ds_read_b128 v[200:203], v179 offset:21504
	ds_read_b128 v[204:207], v179 offset:22528
	ds_read_b128 v[208:211], v179 offset:23552
	s_mov_b32 m0, s16
	s_nop 0
	global_load_lds_dwordx4 v172, s[38:39]
	s_add_i32 m0, s16, 0x2000
	s_add_u32 s50, s38, 0x100000
	global_load_lds_dwordx4 v173, s[38:39]
	s_addc_u32 s51, s39, 0
	s_add_i32 s16, s95, s86
	s_mov_b32 m0, s16
	s_nop 0
	global_load_lds_dwordx4 v172, s[50:51]
	s_add_i32 m0, s16, 0x2000
	s_nop 0
	global_load_lds_dwordx4 v173, s[50:51]
	s_mov_b32 m0, s87
	s_nop 0
	global_load_lds_dwordx4 v172, s[34:35]
	s_mov_b32 m0, s88
	s_nop 0
	global_load_lds_dwordx4 v173, s[34:35]
	s_waitcnt vmcnt(8)
	s_waitcnt lgkmcnt(0)
	s_barrier
	s_setprio 1
	s_waitcnt lgkmcnt(0)
	v_mfma_f32_16x16x32_bf16 v[60:63], v[134:137], v[166:169], v[60:63]
	v_mfma_f32_16x16x32_bf16 v[56:59], v[142:145], v[166:169], v[56:59]
	v_mfma_f32_16x16x32_bf16 v[44:47], v[134:137], v[188:191], v[44:47]
	v_mfma_f32_16x16x32_bf16 v[40:43], v[142:145], v[188:191], v[40:43]
	v_mfma_f32_16x16x32_bf16 v[28:31], v[134:137], v[196:199], v[28:31]
	v_mfma_f32_16x16x32_bf16 v[24:27], v[142:145], v[196:199], v[24:27]
	v_mfma_f32_16x16x32_bf16 v[12:15], v[134:137], v[204:207], v[12:15]
	v_mfma_f32_16x16x32_bf16 v[8:11], v[142:145], v[204:207], v[8:11]
	v_mfma_f32_16x16x32_bf16 v[60:63], v[138:141], v[184:187], v[60:63]
	v_mfma_f32_16x16x32_bf16 v[56:59], v[146:149], v[184:187], v[56:59]
	v_mfma_f32_16x16x32_bf16 v[44:47], v[138:141], v[192:195], v[44:47]
	v_mfma_f32_16x16x32_bf16 v[40:43], v[146:149], v[192:195], v[40:43]
	v_mfma_f32_16x16x32_bf16 v[28:31], v[138:141], v[200:203], v[28:31]
	v_mfma_f32_16x16x32_bf16 v[24:27], v[146:149], v[200:203], v[24:27]
	v_mfma_f32_16x16x32_bf16 v[12:15], v[138:141], v[208:211], v[12:15]
	v_mfma_f32_16x16x32_bf16 v[8:11], v[146:149], v[208:211], v[8:11]
	v_mfma_f32_16x16x32_bf16 v[52:55], v[150:153], v[166:169], v[52:55]
	v_mfma_f32_16x16x32_bf16 v[48:51], v[158:161], v[166:169], v[48:51]
	v_mfma_f32_16x16x32_bf16 v[36:39], v[150:153], v[188:191], v[36:39]
	v_mfma_f32_16x16x32_bf16 v[32:35], v[158:161], v[188:191], v[32:35]
	v_mfma_f32_16x16x32_bf16 v[20:23], v[150:153], v[196:199], v[20:23]
	v_mfma_f32_16x16x32_bf16 v[16:19], v[158:161], v[196:199], v[16:19]
	v_mfma_f32_16x16x32_bf16 v[4:7], v[150:153], v[204:207], v[4:7]
	v_mfma_f32_16x16x32_bf16 v[0:3], v[158:161], v[204:207], v[0:3]
	v_mfma_f32_16x16x32_bf16 v[52:55], v[154:157], v[184:187], v[52:55]
	v_mfma_f32_16x16x32_bf16 v[48:51], v[162:165], v[184:187], v[48:51]
	v_mfma_f32_16x16x32_bf16 v[36:39], v[154:157], v[192:195], v[36:39]
	v_mfma_f32_16x16x32_bf16 v[32:35], v[162:165], v[192:195], v[32:35]
	v_mfma_f32_16x16x32_bf16 v[20:23], v[154:157], v[200:203], v[20:23]
	v_mfma_f32_16x16x32_bf16 v[16:19], v[162:165], v[200:203], v[16:19]
	v_mfma_f32_16x16x32_bf16 v[4:7], v[154:157], v[208:211], v[4:7]
	v_mfma_f32_16x16x32_bf16 v[0:3], v[162:165], v[208:211], v[0:3]
	s_setprio 0
	s_barrier
; #define PG8_LDA(dst, b, h) do { if constexpr (FP8) { _Pragma("unroll") for (int m = 0; m < 4; ++m) dst##8[m] = PG8_LD8(PG8_SA(b, h), aoff, aoff1, m); } \
;         else { _Pragma("unroll") for (int m = 0; m < 4; ++m) _Pragma("unroll") for (int k = 0; k < 2; ++k) dst[m][k] = *(const LAS bf16x8*)(lds + PG8_SA(b, h) + (k ? aoff1 : aoff) + m * 2048); } } while (0)
; #define PG8_LDB(dst, b, h) do { if constexpr (FP8) { dst##8[0] = PG8_LD8(PG8_SB(b, h), boff, boff1, 0); dst##8[1] = PG8_LD8(PG8_SB(b, h), boff, boff1, 1); } \
;         else { _Pragma("unroll") for (int n = 0; n < 2; ++n) _Pragma("unroll") for (int k = 0; k < 2; ++k) dst[n][k] = *(const LAS bf16x8*)(lds + PG8_SB(b, h) + (k ? boff1 : boff) + n * 2048); } } while (0)
; #define PG8_WAIT_V(n) asm volatile("s_waitcnt vmcnt(" #n ")" ::: "memory")
; #define PG8_WAIT_L(n) asm volatile("s_waitcnt lgkmcnt(" #n ")" ::: "memory")
; #define PG8_BAR __builtin_amdgcn_s_barrier()
; #define PG8_SCHED __builtin_amdgcn_sched_barrier(0)
; #define PG8_S3 PG8_STAGE(PG8_SA(0, 1), a2 + hstepA, voffA)
; #define PG8_S4 do { PG8_STAGE(PG8_SB(1, 0), b3, voffB); PG8_STAGE(PG8_SB(1, 1), b3 + hstepB, voffB); PG8_STAGE(PG8_SA(1, 0), a3, voffA); } while (0)
; template <class Epi, class SchedT, bool ALIGN_EPI, bool SP2, bool FP8 = false>
; __device__ __forceinline__ void gemm_phase(LAS unsigned char* lds, const Gemm g, const SchedT& S, const Epi& E, const int wid) {
;     ...
;         for (int t = 0; t < nt; t += 2) {
;     ...
;             PG8_LDB(B0, 1, 0); PG8_LDB(B1, 1, 1); PG8_SCHED; PG8_LDA(At, 1, 0); PG8_S3;
;             PG8_WAIT_V(8); PG8_WAIT_L(0); PG8_BAR; PG8_MMAP(0, 1, 0); PG8_BAR; PG8_SCHED;
;             PG8_LDA(At, 1, 1); PG8_S4;
;             PG8_WAIT_V(8); PG8_WAIT_L(0); PG8_BAR; PG8_MMAP(1, 1, 1); PG8_BAR; PG8_SCHED;
	s_add_i32 s16, 0, 0x18000
	v_add_u32_e32 v128, s16, v174
	s_add_i32 s17, 0, 0x1c000
	ds_read_b128 v[134:137], v128
	ds_read_b128 v[138:141], v128 offset:1024
	ds_read_b128 v[142:145], v180
	ds_read_b128 v[146:149], v180 offset:1024
	v_add_u32_e32 v128, s17, v174
	ds_read_b128 v[150:153], v128
	ds_read_b128 v[154:157], v128 offset:1024
	ds_read_b128 v[158:161], v181
	ds_read_b128 v[162:165], v181 offset:1024
	s_add_u32 s50, s34, 0x100000
	s_mov_b32 m0, s89
	ds_read_b128 v[166:169], v179 offset:32768
	ds_read_b128 v[184:187], v179 offset:33792
	ds_read_b128 v[188:191], v179 offset:34816
	ds_read_b128 v[192:195], v179 offset:35840
	ds_read_b128 v[196:199], v179 offset:36864
	ds_read_b128 v[200:203], v179 offset:37888
	ds_read_b128 v[204:207], v179 offset:38912
	ds_read_b128 v[208:211], v179 offset:39936
	s_addc_u32 s51, s35, 0
	s_nop 0
	global_load_lds_dwordx4 v172, s[50:51]
	s_mov_b32 m0, s90
	s_nop 0
	global_load_lds_dwordx4 v173, s[50:51]
	s_waitcnt vmcnt(8)
	s_waitcnt lgkmcnt(0)
	s_barrier
	s_setprio 1
	s_waitcnt lgkmcnt(0)
	v_mfma_f32_16x16x32_bf16 v[124:127], v[134:137], v[166:169], v[124:127]
	v_mfma_f32_16x16x32_bf16 v[120:123], v[142:145], v[166:169], v[120:123]
	v_mfma_f32_16x16x32_bf16 v[108:111], v[134:137], v[188:191], v[108:111]
	v_mfma_f32_16x16x32_bf16 v[104:107], v[142:145], v[188:191], v[104:107]
	v_mfma_f32_16x16x32_bf16 v[92:95], v[134:137], v[196:199], v[92:95]
	v_mfma_f32_16x16x32_bf16 v[88:91], v[142:145], v[196:199], v[88:91]
	v_mfma_f32_16x16x32_bf16 v[76:79], v[134:137], v[204:207], v[76:79]
	v_mfma_f32_16x16x32_bf16 v[72:75], v[142:145], v[204:207], v[72:75]
	v_mfma_f32_16x16x32_bf16 v[124:127], v[138:141], v[184:187], v[124:127]
	v_mfma_f32_16x16x32_bf16 v[120:123], v[146:149], v[184:187], v[120:123]
	v_mfma_f32_16x16x32_bf16 v[108:111], v[138:141], v[192:195], v[108:111]
	v_mfma_f32_16x16x32_bf16 v[104:107], v[146:149], v[192:195], v[104:107]
	v_mfma_f32_16x16x32_bf16 v[92:95], v[138:141], v[200:203], v[92:95]
	v_mfma_f32_16x16x32_bf16 v[88:91], v[146:149], v[200:203], v[88:91]
	v_mfma_f32_16x16x32_bf16 v[76:79], v[138:141], v[208:211], v[76:79]
	v_mfma_f32_16x16x32_bf16 v[72:75], v[146:149], v[208:211], v[72:75]
	v_mfma_f32_16x16x32_bf16 v[116:119], v[150:153], v[166:169], v[116:119]
	v_mfma_f32_16x16x32_bf16 v[112:115], v[158:161], v[166:169], v[112:115]
	v_mfma_f32_16x16x32_bf16 v[100:103], v[150:153], v[188:191], v[100:103]
	v_mfma_f32_16x16x32_bf16 v[96:99], v[158:161], v[188:191], v[96:99]
	v_mfma_f32_16x16x32_bf16 v[84:87], v[150:153], v[196:199], v[84:87]
	v_mfma_f32_16x16x32_bf16 v[80:83], v[158:161], v[196:199], v[80:83]
	v_mfma_f32_16x16x32_bf16 v[68:71], v[150:153], v[204:207], v[68:71]
	v_mfma_f32_16x16x32_bf16 v[64:67], v[158:161], v[204:207], v[64:67]
	v_mfma_f32_16x16x32_bf16 v[116:119], v[154:157], v[184:187], v[116:119]
	v_mfma_f32_16x16x32_bf16 v[112:115], v[162:165], v[184:187], v[112:115]
	v_mfma_f32_16x16x32_bf16 v[100:103], v[154:157], v[192:195], v[100:103]
	v_mfma_f32_16x16x32_bf16 v[96:99], v[162:165], v[192:195], v[96:99]
	v_mfma_f32_16x16x32_bf16 v[84:87], v[154:157], v[200:203], v[84:87]
	v_mfma_f32_16x16x32_bf16 v[80:83], v[162:165], v[200:203], v[80:83]
	v_mfma_f32_16x16x32_bf16 v[68:71], v[154:157], v[208:211], v[68:71]
	v_mfma_f32_16x16x32_bf16 v[64:67], v[162:165], v[208:211], v[64:67]
	s_setprio 0
	s_barrier
	ds_read_b128 v[166:169], v179 offset:49152
	ds_read_b128 v[184:187], v179 offset:50176
	ds_read_b128 v[188:191], v179 offset:51200
	ds_read_b128 v[192:195], v179 offset:52224
	ds_read_b128 v[196:199], v179 offset:53248
	ds_read_b128 v[200:203], v179 offset:54272
	ds_read_b128 v[204:207], v179 offset:55296
	ds_read_b128 v[208:211], v179 offset:56320
	s_add_i32 s16, s16, s86
	s_add_u32 s98, s38, s8
	s_addc_u32 s99, s39, s9
	s_mov_b32 m0, s16
	s_nop 0
	global_load_lds_dwordx4 v172, s[98:99]
	s_add_i32 m0, s16, 0x2000
	s_nop 0
	s_add_u32 s38, s38, 0x100080
	s_addc_u32 s39, s39, 0
	s_add_i32 s16, s17, s86
	global_load_lds_dwordx4 v173, s[98:99]
	s_mov_b32 m0, s16
	s_nop 0
	global_load_lds_dwordx4 v172, s[38:39]
	s_add_i32 m0, s16, 0x2000
	s_nop 0
	global_load_lds_dwordx4 v173, s[38:39]
	s_mov_b32 m0, s92
	s_add_u32 s100, s34, s8
	s_addc_u32 s101, s35, s9
	global_load_lds_dwordx4 v172, s[100:101]
	s_mov_b32 m0, s93
	s_nop 0
	global_load_lds_dwordx4 v173, s[100:101]
	s_waitcnt vmcnt(8)
	s_waitcnt lgkmcnt(0)
	s_barrier
	s_setprio 1
	s_waitcnt lgkmcnt(0)
	v_mfma_f32_16x16x32_bf16 v[60:63], v[134:137], v[166:169], v[60:63]
	v_mfma_f32_16x16x32_bf16 v[56:59], v[142:145], v[166:169], v[56:59]
	v_mfma_f32_16x16x32_bf16 v[44:47], v[134:137], v[188:191], v[44:47]
	v_mfma_f32_16x16x32_bf16 v[40:43], v[142:145], v[188:191], v[40:43]
	v_mfma_f32_16x16x32_bf16 v[28:31], v[134:137], v[196:199], v[28:31]
	v_mfma_f32_16x16x32_bf16 v[24:27], v[142:145], v[196:199], v[24:27]
	v_mfma_f32_16x16x32_bf16 v[12:15], v[134:137], v[204:207], v[12:15]
	v_mfma_f32_16x16x32_bf16 v[8:11], v[142:145], v[204:207], v[8:11]
	v_mfma_f32_16x16x32_bf16 v[60:63], v[138:141], v[184:187], v[60:63]
	v_mfma_f32_16x16x32_bf16 v[56:59], v[146:149], v[184:187], v[56:59]
	v_mfma_f32_16x16x32_bf16 v[44:47], v[138:141], v[192:195], v[44:47]
	v_mfma_f32_16x16x32_bf16 v[40:43], v[146:149], v[192:195], v[40:43]
	v_mfma_f32_16x16x32_bf16 v[28:31], v[138:141], v[200:203], v[28:31]
	v_mfma_f32_16x16x32_bf16 v[24:27], v[146:149], v[200:203], v[24:27]
	v_mfma_f32_16x16x32_bf16 v[12:15], v[138:141], v[208:211], v[12:15]
	v_mfma_f32_16x16x32_bf16 v[8:11], v[146:149], v[208:211], v[8:11]
	v_mfma_f32_16x16x32_bf16 v[52:55], v[150:153], v[166:169], v[52:55]
	v_mfma_f32_16x16x32_bf16 v[48:51], v[158:161], v[166:169], v[48:51]
	v_mfma_f32_16x16x32_bf16 v[36:39], v[150:153], v[188:191], v[36:39]
	v_mfma_f32_16x16x32_bf16 v[32:35], v[158:161], v[188:191], v[32:35]
	v_mfma_f32_16x16x32_bf16 v[20:23], v[150:153], v[196:199], v[20:23]
	v_mfma_f32_16x16x32_bf16 v[16:19], v[158:161], v[196:199], v[16:19]
	v_mfma_f32_16x16x32_bf16 v[4:7], v[150:153], v[204:207], v[4:7]
	v_mfma_f32_16x16x32_bf16 v[0:3], v[158:161], v[204:207], v[0:3]
	v_mfma_f32_16x16x32_bf16 v[52:55], v[154:157], v[184:187], v[52:55]
	v_mfma_f32_16x16x32_bf16 v[48:51], v[162:165], v[184:187], v[48:51]
	v_mfma_f32_16x16x32_bf16 v[36:39], v[154:157], v[192:195], v[36:39]
	v_mfma_f32_16x16x32_bf16 v[32:35], v[162:165], v[192:195], v[32:35]
	v_mfma_f32_16x16x32_bf16 v[20:23], v[154:157], v[200:203], v[20:23]
	v_mfma_f32_16x16x32_bf16 v[16:19], v[162:165], v[200:203], v[16:19]
	v_mfma_f32_16x16x32_bf16 v[4:7], v[154:157], v[208:211], v[4:7]
	v_mfma_f32_16x16x32_bf16 v[0:3], v[162:165], v[208:211], v[0:3]
	s_setprio 0
	s_barrier
	s_add_u32 s24, s24, 0x100
	s_addc_u32 s25, s25, 0
	s_add_u32 s46, s46, 0x100
	s_addc_u32 s47, s47, 0
	s_cmp_ge_i32 s48, s30
	s_mov_b32 s34, s48
	s_cbranch_scc0 .LBB0_970
	s_and_b64 vcc, exec, s[96:97]
	s_cbranch_vccz .LBB0_973

; __global__ void __launch_bounds__(512, 2) fwd_megakernel(Args args) {
	.amdhsa_kernel _Z14fwd_megakernel4Args
		.amdhsa_group_segment_fixed_size 0
		.amdhsa_private_segment_fixed_size 0
		.amdhsa_kernarg_size 416
		.amdhsa_user_sgpr_count 2
		.amdhsa_user_sgpr_dispatch_ptr 0
		.amdhsa_user_sgpr_queue_ptr 0
		.amdhsa_user_sgpr_kernarg_segment_ptr 1
		.amdhsa_user_sgpr_dispatch_id 0
		.amdhsa_user_sgpr_kernarg_preload_length 0
		.amdhsa_user_sgpr_kernarg_preload_offset 0
		.amdhsa_user_sgpr_private_segment_size 0
		.amdhsa_uses_dynamic_stack 0
		.amdhsa_enable_private_segment 0
		.amdhsa_system_sgpr_workgroup_id_x 1
		.amdhsa_system_sgpr_workgroup_id_y 0
		.amdhsa_system_sgpr_workgroup_id_z 0
		.amdhsa_system_sgpr_workgroup_info 0
		.amdhsa_system_vgpr_workitem_id 2
		.amdhsa_next_free_vgpr 250
		.amdhsa_next_free_sgpr 102
		.amdhsa_accum_offset 252
		.amdhsa_reserve_vcc 1
		.amdhsa_float_round_mode_32 0
		.amdhsa_float_round_mode_16_64 0
		.amdhsa_float_denorm_mode_32 3
		.amdhsa_float_denorm_mode_16_64 3
		.amdhsa_dx10_clamp 1
		.amdhsa_ieee_mode 1
		.amdhsa_fp16_overflow 0
		.amdhsa_tg_split 0
		.amdhsa_exception_fp_ieee_invalid_op 0
		.amdhsa_exception_fp_denorm_src 0
		.amdhsa_exception_fp_ieee_div_zero 0
		.amdhsa_exception_fp_ieee_overflow 0
		.amdhsa_exception_fp_ieee_underflow 0
		.amdhsa_exception_fp_ieee_inexact 0
		.amdhsa_exception_int_div_zero 0
	.end_amdhsa_kernel

; __global__ void __launch_bounds__(512, 2) fwd_megakernel(Args args) {
amdhsa.kernels:
  - .agpr_count:     0
    .args:
      - .offset:         0
        .size:           160
        .value_kind:     by_value
      - .offset:         160
        .size:           4
        .value_kind:     hidden_block_count_x
      - .offset:         164
        .size:           4
        .value_kind:     hidden_block_count_y
      - .offset:         168
        .size:           4
        .value_kind:     hidden_block_count_z
      - .offset:         172
        .size:           2
        .value_kind:     hidden_group_size_x
      - .offset:         174
        .size:           2
        .value_kind:     hidden_group_size_y
      - .offset:         176
        .size:           2
        .value_kind:     hidden_group_size_z
      - .offset:         178
        .size:           2
        .value_kind:     hidden_remainder_x
      - .offset:         180
        .size:           2
        .value_kind:     hidden_remainder_y
      - .offset:         182
        .size:           2
        .value_kind:     hidden_remainder_z
      - .offset:         200
        .size:           8
        .value_kind:     hidden_global_offset_x
      - .offset:         208
        .size:           8
        .value_kind:     hidden_global_offset_y
      - .offset:         216
        .size:           8
        .value_kind:     hidden_global_offset_z
      - .offset:         224
        .size:           2
        .value_kind:     hidden_grid_dims
      - .offset:         248
        .size:           8
        .value_kind:     hidden_multigrid_sync_arg
      - .offset:         280
        .size:           4
        .value_kind:     hidden_dynamic_lds_size
    .group_segment_fixed_size: 0
    .kernarg_segment_align: 8
    .kernarg_segment_size: 416
    .language:       OpenCL C
    .language_version:
      - 2
      - 0
    .max_flat_workgroup_size: 512
    .name:           _Z14fwd_megakernel4Args
    .private_segment_fixed_size: 0
    .sgpr_count:     108
    .sgpr_spill_count: 83
    .symbol:         _Z14fwd_megakernel4Args.kd
    .uniform_work_group_size: 1
    .uses_dynamic_stack: false
    .vgpr_count:     250
    .vgpr_spill_count: 0
    .wavefront_size: 64
